# rmsnorm phases: weight vectors loaded once per phase, next row prefetched before the stores (no per-chunk store-ack waits)
# speedup vs baseline: 1.0517x; 1.0066x over previous
.LBB0_727:
	s_nop 0
	v_mov_b32_e32 v0, s4
	ds_read_b64 v[0:1], v0 offset:56
	s_waitcnt lgkmcnt(0)
	v_readfirstlane_b32 s3, v1
	v_readfirstlane_b32 s2, v0
	s_cmp_eq_u64 s[2:3], 0
	s_cbranch_scc1 .LBB0_781
	v_mov_b32_e32 v4, s4
	ds_read_b128 v[0:3], v4 offset:64
	ds_read_b128 v[4:7], v4 offset:80
	v_readlane_b32 s7, v246, 22
	s_waitcnt lgkmcnt(0)
	v_readfirstlane_b32 s4, v0
	v_mov_b32_e32 v0, v149
	v_readfirstlane_b32 s5, v1
	v_readfirstlane_b32 s9, v3
	v_ashrrev_i32_e32 v1, 6, v0
	s_waitcnt vmcnt(0)
	v_add_u32_e32 v38, s7, v1
	v_readfirstlane_b32 s8, v2
	v_readfirstlane_b32 s13, v5
	v_readfirstlane_b32 s12, v4
	v_readfirstlane_b32 s15, v7
	v_readfirstlane_b32 s14, v6
	v_mov_b32_e32 v0, v149
	v_cmp_gt_i32_e32 vcc, s80, v38
	s_and_saveexec_b64 s[16:17], vcc
	s_cbranch_execz .LBB0_780
	v_lshlrev_b32_e32 v0, 2, v0
	v_and_b32_e32 v40, 0xfc, v0
	v_lshlrev_b32_e32 v4, 2, v40
	v_mov_b32_e32 v5, v28
	v_lshl_add_u64 v[42:43], s[2:3], 0, v[4:5]
	flat_load_dwordx4 v[0:3], v[42:43]
	v_and_b32_e32 v6, 64, v205
	v_add_u32_e32 v6, 64, v6
	v_xor_b32_e32 v7, 32, v205
	v_cmp_lt_i32_e32 vcc, v7, v6
	v_lshl_add_u64 v[44:45], s[0:1], 0, v[4:5]
	v_lshl_add_u64 v[46:47], s[8:9], 0, v[4:5]
	v_cndmask_b32_e32 v7, v205, v7, vcc
	v_lshlrev_b32_e32 v29, 2, v7
	v_xor_b32_e32 v7, 16, v205
	v_cmp_lt_i32_e32 vcc, v7, v6
	v_or_b32_e32 v4, 0x400, v40
	v_mov_b32_e32 v9, v28
	v_cndmask_b32_e32 v7, v205, v7, vcc
	v_lshlrev_b32_e32 v41, 2, v7
	v_xor_b32_e32 v7, 8, v205
	v_cmp_lt_i32_e32 vcc, v7, v6
	v_mov_b32_e32 v11, v28
	s_cmp_lg_u64 s[14:15], 0
	v_cndmask_b32_e32 v7, v205, v7, vcc
	v_lshlrev_b32_e32 v86, 2, v7
	v_xor_b32_e32 v7, 4, v205
	v_cmp_lt_i32_e32 vcc, v7, v6
	s_cselect_b64 s[20:21], -1, 0
	s_cmp_lg_u64 s[8:9], 0
	v_cndmask_b32_e32 v7, v205, v7, vcc
	v_lshlrev_b32_e32 v87, 2, v7
	v_xor_b32_e32 v7, 2, v205
	v_cmp_lt_i32_e32 vcc, v7, v6
	v_mov_b32_e32 v13, v28
	s_mov_b64 s[18:19], 0
	v_cndmask_b32_e32 v7, v205, v7, vcc
	v_lshlrev_b32_e32 v88, 2, v7
	v_xor_b32_e32 v7, 1, v205
	v_cmp_lt_i32_e32 vcc, v7, v6
	s_cselect_b64 s[22:23], -1, 0
	v_lshlrev_b32_e32 v64, 2, v4
	v_cndmask_b32_e32 v6, v205, v7, vcc
	v_lshlrev_b32_e32 v89, 2, v6
	v_lshlrev_b32_e32 v6, 2, v4
	v_mov_b32_e32 v7, v28
	v_lshl_add_u64 v[48:49], s[2:3], 0, v[6:7]
	v_lshl_add_u64 v[50:51], s[8:9], 0, v[6:7]
	v_or_b32_e32 v6, 0x500, v40
	v_lshlrev_b32_e32 v8, 2, v6
	v_lshl_add_u64 v[52:53], s[2:3], 0, v[8:9]
	v_lshl_add_u64 v[54:55], s[8:9], 0, v[8:9]
	v_or_b32_e32 v8, 0x600, v40
	v_lshlrev_b32_e32 v10, 2, v8
	v_lshl_add_u64 v[56:57], s[2:3], 0, v[10:11]
	v_lshl_add_u64 v[58:59], s[8:9], 0, v[10:11]
	v_or_b32_e32 v10, 0x700, v40
	v_lshlrev_b32_e32 v12, 2, v10
	v_lshl_add_u64 v[60:61], s[2:3], 0, v[12:13]
	v_lshl_add_u64 v[62:63], s[8:9], 0, v[12:13]
	v_lshlrev_b32_e32 v66, 2, v6
	v_lshlrev_b32_e32 v68, 2, v8
	v_lshlrev_b32_e32 v70, 2, v10
	v_lshlrev_b32_e32 v80, 2, v40
	v_mov_b32_e32 v81, v28
	v_lshlrev_b32_e32 v70, 1, v40
	v_mov_b32_e32 v71, v28
	global_load_dwordx4 v[96:99], v[42:43], off offset:1024
	global_load_dwordx4 v[100:103], v[42:43], off offset:2048
	global_load_dwordx4 v[104:107], v[42:43], off offset:3072
	global_load_dwordx4 v[108:111], v[48:49], off
	global_load_dwordx4 v[112:115], v[52:53], off
	global_load_dwordx4 v[116:119], v[56:57], off
	global_load_dwordx4 v[120:123], v[60:61], off
	s_and_b64 vcc, exec, s[22:23]
	s_cbranch_vccz .Lnp_nog2
	global_load_dwordx4 v[152:155], v[46:47], off
	global_load_dwordx4 v[156:159], v[46:47], off offset:1024
	global_load_dwordx4 v[160:163], v[46:47], off offset:2048
	global_load_dwordx4 v[164:167], v[46:47], off offset:3072
	global_load_dwordx4 v[168:171], v[50:51], off
	global_load_dwordx4 v[172:175], v[54:55], off
	global_load_dwordx4 v[176:179], v[58:59], off
	global_load_dwordx4 v[180:183], v[62:63], off
.Lnp_nog2:
	v_ashrrev_i32_e32 v39, 31, v38
	v_lshlrev_b64 v[72:73], 13, v[38:39]
	v_lshl_add_u64 v[66:67], v[44:45], 0, v[72:73]
	s_movk_i32 s0, 0x1000
	s_mov_b32 s1, 0
	v_lshl_add_u64 v[68:69], v[66:67], 0, s[0:1]
	global_load_dwordx4 v[34:37], v[66:67], off
	global_load_dwordx4 v[30:33], v[66:67], off offset:1024
	global_load_dwordx4 v[24:27], v[66:67], off offset:2048
	global_load_dwordx4 v[20:23], v[66:67], off offset:3072
	global_load_dwordx4 v[16:19], v[68:69], off
	global_load_dwordx4 v[12:15], v[68:69], off offset:1024
	global_load_dwordx4 v[8:11], v[68:69], off offset:2048
	global_load_dwordx4 v[4:7], v[68:69], off offset:3072
	s_waitcnt vmcnt(0)
	s_and_b64 vcc, exec, s[20:21]
	s_cbranch_vccnz .Lnp_C_body
	s_and_b64 vcc, exec, s[22:23]
	s_cbranch_vccnz .Lnp_B_body
.Lnp_A_body:
	v_pk_mul_f32 v[74:75], v[34:35], v[34:35]
	v_pk_fma_f32 v[74:75], v[36:37], v[36:37], v[74:75]
	v_pk_fma_f32 v[74:75], v[30:31], v[30:31], v[74:75]
	v_pk_fma_f32 v[74:75], v[32:33], v[32:33], v[74:75]
	v_pk_fma_f32 v[74:75], v[24:25], v[24:25], v[74:75]
	v_pk_fma_f32 v[74:75], v[26:27], v[26:27], v[74:75]
	v_pk_fma_f32 v[74:75], v[20:21], v[20:21], v[74:75]
	v_pk_fma_f32 v[74:75], v[22:23], v[22:23], v[74:75]
	v_pk_fma_f32 v[74:75], v[16:17], v[16:17], v[74:75]
	v_pk_fma_f32 v[74:75], v[18:19], v[18:19], v[74:75]
	v_pk_fma_f32 v[74:75], v[12:13], v[12:13], v[74:75]
	v_pk_fma_f32 v[74:75], v[14:15], v[14:15], v[74:75]
	v_pk_fma_f32 v[74:75], v[8:9], v[8:9], v[74:75]
	v_pk_fma_f32 v[74:75], v[10:11], v[10:11], v[74:75]
	v_pk_fma_f32 v[74:75], v[4:5], v[4:5], v[74:75]
	v_pk_fma_f32 v[74:75], v[6:7], v[6:7], v[74:75]
	v_add_f32_e32 v65, v74, v75
	ds_bpermute_b32 v67, v29, v65
	s_waitcnt lgkmcnt(0)
	v_add_f32_e32 v65, v65, v67
	ds_bpermute_b32 v67, v41, v65
	s_waitcnt lgkmcnt(0)
	v_add_f32_e32 v65, v65, v67
	ds_bpermute_b32 v67, v86, v65
	s_waitcnt lgkmcnt(0)
	v_add_f32_e32 v65, v65, v67
	ds_bpermute_b32 v67, v87, v65
	s_waitcnt lgkmcnt(0)
	v_add_f32_e32 v65, v65, v67
	ds_bpermute_b32 v67, v88, v65
	s_waitcnt lgkmcnt(0)
	v_add_f32_e32 v65, v65, v67
	ds_bpermute_b32 v67, v89, v65
	s_waitcnt lgkmcnt(0)
	v_add_f32_e32 v65, v65, v67
	v_fmamk_f32 v65, v65, 0x3a000000, v148
	v_mul_f32_e32 v67, 0x4b800000, v65
	v_cmp_gt_f32_e64 s[0:1], s81, v65
	s_nop 1
	v_cndmask_b32_e64 v65, v65, v67, s[0:1]
	v_rsq_f32_e32 v65, v65
	s_nop 0
	v_mul_f32_e32 v67, 0x45800000, v65
	v_cndmask_b32_e64 v78, v65, v67, s[0:1]
	v_lshlrev_b64 v[82:83], 12, v[38:39]
	v_lshl_add_u64 v[76:77], s[4:5], 0, v[82:83]
	v_lshl_add_u64 v[76:77], v[76:77], 0, v[70:71]
	v_pk_mul_f32 v[84:85], v[34:35], v[78:79] op_sel_hi:[1,0]
	v_pk_mul_f32 v[90:91], v[36:37], v[78:79] op_sel_hi:[1,0]
	v_pk_mul_f32 v[130:131], v[0:1], v[84:85]
	v_pk_mul_f32 v[132:133], v[2:3], v[90:91]
	v_cvt_pk_bf16_f32 v130, v130, v131
	s_nop 0
	v_cvt_pk_bf16_f32 v131, v132, v133
	v_pk_mul_f32 v[84:85], v[30:31], v[78:79] op_sel_hi:[1,0]
	v_pk_mul_f32 v[90:91], v[32:33], v[78:79] op_sel_hi:[1,0]
	v_pk_mul_f32 v[134:135], v[96:97], v[84:85]
	v_pk_mul_f32 v[136:137], v[98:99], v[90:91]
	v_cvt_pk_bf16_f32 v134, v134, v135
	s_nop 0
	v_cvt_pk_bf16_f32 v135, v136, v137
	v_pk_mul_f32 v[84:85], v[24:25], v[78:79] op_sel_hi:[1,0]
	v_pk_mul_f32 v[90:91], v[26:27], v[78:79] op_sel_hi:[1,0]
	v_pk_mul_f32 v[138:139], v[100:101], v[84:85]
	v_pk_mul_f32 v[140:141], v[102:103], v[90:91]
	v_cvt_pk_bf16_f32 v138, v138, v139
	s_nop 0
	v_cvt_pk_bf16_f32 v139, v140, v141
	v_pk_mul_f32 v[84:85], v[20:21], v[78:79] op_sel_hi:[1,0]
	v_pk_mul_f32 v[90:91], v[22:23], v[78:79] op_sel_hi:[1,0]
	v_pk_mul_f32 v[142:143], v[104:105], v[84:85]
	v_pk_mul_f32 v[144:145], v[106:107], v[90:91]
	v_cvt_pk_bf16_f32 v142, v142, v143
	s_nop 0
	v_cvt_pk_bf16_f32 v143, v144, v145
	v_pk_mul_f32 v[84:85], v[16:17], v[78:79] op_sel_hi:[1,0]
	v_pk_mul_f32 v[90:91], v[18:19], v[78:79] op_sel_hi:[1,0]
	v_pk_mul_f32 v[184:185], v[108:109], v[84:85]
	v_pk_mul_f32 v[186:187], v[110:111], v[90:91]
	v_cvt_pk_bf16_f32 v184, v184, v185
	s_nop 0
	v_cvt_pk_bf16_f32 v185, v186, v187
	v_pk_mul_f32 v[84:85], v[12:13], v[78:79] op_sel_hi:[1,0]
	v_pk_mul_f32 v[90:91], v[14:15], v[78:79] op_sel_hi:[1,0]
	v_pk_mul_f32 v[188:189], v[112:113], v[84:85]
	v_pk_mul_f32 v[190:191], v[114:115], v[90:91]
	v_cvt_pk_bf16_f32 v188, v188, v189
	s_nop 0
	v_cvt_pk_bf16_f32 v189, v190, v191
	v_pk_mul_f32 v[84:85], v[8:9], v[78:79] op_sel_hi:[1,0]
	v_pk_mul_f32 v[90:91], v[10:11], v[78:79] op_sel_hi:[1,0]
	v_pk_mul_f32 v[192:193], v[116:117], v[84:85]
	v_pk_mul_f32 v[194:195], v[118:119], v[90:91]
	v_cvt_pk_bf16_f32 v192, v192, v193
	s_nop 0
	v_cvt_pk_bf16_f32 v193, v194, v195
	v_pk_mul_f32 v[84:85], v[4:5], v[78:79] op_sel_hi:[1,0]
	v_pk_mul_f32 v[90:91], v[6:7], v[78:79] op_sel_hi:[1,0]
	v_pk_mul_f32 v[92:93], v[120:121], v[84:85]
	v_pk_mul_f32 v[94:95], v[122:123], v[90:91]
	v_cvt_pk_bf16_f32 v92, v92, v93
	s_nop 0
	v_cvt_pk_bf16_f32 v93, v94, v95
	v_add_u32_e32 v38, s33, v38
	s_nop 0
	v_readfirstlane_b32 s0, v38
	s_cmpk_gt_i32 s0, 0x1fff
	s_cbranch_scc1 .Lnp_A_last
	v_ashrrev_i32_e32 v39, 31, v38
	v_lshlrev_b64 v[72:73], 13, v[38:39]
	v_lshl_add_u64 v[66:67], v[44:45], 0, v[72:73]
	s_movk_i32 s0, 0x1000
	s_mov_b32 s1, 0
	v_lshl_add_u64 v[68:69], v[66:67], 0, s[0:1]
	global_load_dwordx4 v[34:37], v[66:67], off
	global_load_dwordx4 v[30:33], v[66:67], off offset:1024
	global_load_dwordx4 v[24:27], v[66:67], off offset:2048
	global_load_dwordx4 v[20:23], v[66:67], off offset:3072
	global_load_dwordx4 v[16:19], v[68:69], off
	global_load_dwordx4 v[12:15], v[68:69], off offset:1024
	global_load_dwordx4 v[8:11], v[68:69], off offset:2048
	global_load_dwordx4 v[4:7], v[68:69], off offset:3072
	global_store_dwordx2 v[76:77], v[130:131], off
	global_store_dwordx2 v[76:77], v[134:135], off offset:512
	global_store_dwordx2 v[76:77], v[138:139], off offset:1024
	global_store_dwordx2 v[76:77], v[142:143], off offset:1536
	global_store_dwordx2 v[76:77], v[184:185], off offset:2048
	global_store_dwordx2 v[76:77], v[188:189], off offset:2560
	global_store_dwordx2 v[76:77], v[192:193], off offset:3072
	global_store_dwordx2 v[76:77], v[92:93], off offset:3584
	s_waitcnt vmcnt(8)
	s_branch .Lnp_A_body
.Lnp_A_last:
	global_store_dwordx2 v[76:77], v[130:131], off
	global_store_dwordx2 v[76:77], v[134:135], off offset:512
	global_store_dwordx2 v[76:77], v[138:139], off offset:1024
	global_store_dwordx2 v[76:77], v[142:143], off offset:1536
	global_store_dwordx2 v[76:77], v[184:185], off offset:2048
	global_store_dwordx2 v[76:77], v[188:189], off offset:2560
	global_store_dwordx2 v[76:77], v[192:193], off offset:3072
	global_store_dwordx2 v[76:77], v[92:93], off offset:3584
	s_branch .LBB0_780
.Lnp_B_body:
	v_pk_mul_f32 v[74:75], v[34:35], v[34:35]
	v_pk_fma_f32 v[74:75], v[36:37], v[36:37], v[74:75]
	v_pk_fma_f32 v[74:75], v[30:31], v[30:31], v[74:75]
	v_pk_fma_f32 v[74:75], v[32:33], v[32:33], v[74:75]
	v_pk_fma_f32 v[74:75], v[24:25], v[24:25], v[74:75]
	v_pk_fma_f32 v[74:75], v[26:27], v[26:27], v[74:75]
	v_pk_fma_f32 v[74:75], v[20:21], v[20:21], v[74:75]
	v_pk_fma_f32 v[74:75], v[22:23], v[22:23], v[74:75]
	v_pk_fma_f32 v[74:75], v[16:17], v[16:17], v[74:75]
	v_pk_fma_f32 v[74:75], v[18:19], v[18:19], v[74:75]
	v_pk_fma_f32 v[74:75], v[12:13], v[12:13], v[74:75]
	v_pk_fma_f32 v[74:75], v[14:15], v[14:15], v[74:75]
	v_pk_fma_f32 v[74:75], v[8:9], v[8:9], v[74:75]
	v_pk_fma_f32 v[74:75], v[10:11], v[10:11], v[74:75]
	v_pk_fma_f32 v[74:75], v[4:5], v[4:5], v[74:75]
	v_pk_fma_f32 v[74:75], v[6:7], v[6:7], v[74:75]
	v_add_f32_e32 v65, v74, v75
	ds_bpermute_b32 v67, v29, v65
	s_waitcnt lgkmcnt(0)
	v_add_f32_e32 v65, v65, v67
	ds_bpermute_b32 v67, v41, v65
	s_waitcnt lgkmcnt(0)
	v_add_f32_e32 v65, v65, v67
	ds_bpermute_b32 v67, v86, v65
	s_waitcnt lgkmcnt(0)
	v_add_f32_e32 v65, v65, v67
	ds_bpermute_b32 v67, v87, v65
	s_waitcnt lgkmcnt(0)
	v_add_f32_e32 v65, v65, v67
	ds_bpermute_b32 v67, v88, v65
	s_waitcnt lgkmcnt(0)
	v_add_f32_e32 v65, v65, v67
	ds_bpermute_b32 v67, v89, v65
	s_waitcnt lgkmcnt(0)
	v_add_f32_e32 v65, v65, v67
	v_fmamk_f32 v65, v65, 0x3a000000, v148
	v_mul_f32_e32 v67, 0x4b800000, v65
	v_cmp_gt_f32_e64 s[0:1], s81, v65
	s_nop 1
	v_cndmask_b32_e64 v65, v65, v67, s[0:1]
	v_rsq_f32_e32 v65, v65
	s_nop 0
	v_mul_f32_e32 v67, 0x45800000, v65
	v_cndmask_b32_e64 v78, v65, v67, s[0:1]
	v_lshlrev_b64 v[82:83], 12, v[38:39]
	v_lshl_add_u64 v[76:77], s[4:5], 0, v[82:83]
	v_lshl_add_u64 v[76:77], v[76:77], 0, v[70:71]
	v_lshl_add_u64 v[128:129], s[12:13], 0, v[82:83]
	v_lshl_add_u64 v[128:129], v[128:129], 0, v[70:71]
	v_pk_mul_f32 v[84:85], v[34:35], v[78:79] op_sel_hi:[1,0]
	v_pk_mul_f32 v[90:91], v[36:37], v[78:79] op_sel_hi:[1,0]
	v_pk_mul_f32 v[130:131], v[0:1], v[84:85]
	v_pk_mul_f32 v[132:133], v[2:3], v[90:91]
	v_cvt_pk_bf16_f32 v130, v130, v131
	s_nop 0
	v_cvt_pk_bf16_f32 v131, v132, v133
	v_pk_mul_f32 v[124:125], v[84:85], v[152:153]
	v_pk_mul_f32 v[126:127], v[90:91], v[154:155]
	v_cvt_pk_bf16_f32 v132, v124, v125
	s_nop 0
	v_cvt_pk_bf16_f32 v133, v126, v127
	v_pk_mul_f32 v[84:85], v[30:31], v[78:79] op_sel_hi:[1,0]
	v_pk_mul_f32 v[90:91], v[32:33], v[78:79] op_sel_hi:[1,0]
	v_pk_mul_f32 v[134:135], v[96:97], v[84:85]
	v_pk_mul_f32 v[136:137], v[98:99], v[90:91]
	v_cvt_pk_bf16_f32 v134, v134, v135
	s_nop 0
	v_cvt_pk_bf16_f32 v135, v136, v137
	v_pk_mul_f32 v[124:125], v[84:85], v[156:157]
	v_pk_mul_f32 v[126:127], v[90:91], v[158:159]
	v_cvt_pk_bf16_f32 v136, v124, v125
	s_nop 0
	v_cvt_pk_bf16_f32 v137, v126, v127
	v_pk_mul_f32 v[84:85], v[24:25], v[78:79] op_sel_hi:[1,0]
	v_pk_mul_f32 v[90:91], v[26:27], v[78:79] op_sel_hi:[1,0]
	v_pk_mul_f32 v[138:139], v[100:101], v[84:85]
	v_pk_mul_f32 v[140:141], v[102:103], v[90:91]
	v_cvt_pk_bf16_f32 v138, v138, v139
	s_nop 0
	v_cvt_pk_bf16_f32 v139, v140, v141
	v_pk_mul_f32 v[124:125], v[84:85], v[160:161]
	v_pk_mul_f32 v[126:127], v[90:91], v[162:163]
	v_cvt_pk_bf16_f32 v140, v124, v125
	s_nop 0
	v_cvt_pk_bf16_f32 v141, v126, v127
	v_pk_mul_f32 v[84:85], v[20:21], v[78:79] op_sel_hi:[1,0]
	v_pk_mul_f32 v[90:91], v[22:23], v[78:79] op_sel_hi:[1,0]
	v_pk_mul_f32 v[142:143], v[104:105], v[84:85]
	v_pk_mul_f32 v[144:145], v[106:107], v[90:91]
	v_cvt_pk_bf16_f32 v142, v142, v143
	s_nop 0
	v_cvt_pk_bf16_f32 v143, v144, v145
	v_pk_mul_f32 v[124:125], v[84:85], v[164:165]
	v_pk_mul_f32 v[126:127], v[90:91], v[166:167]
	v_cvt_pk_bf16_f32 v144, v124, v125
	s_nop 0
	v_cvt_pk_bf16_f32 v145, v126, v127
	v_pk_mul_f32 v[84:85], v[16:17], v[78:79] op_sel_hi:[1,0]
	v_pk_mul_f32 v[90:91], v[18:19], v[78:79] op_sel_hi:[1,0]
	v_pk_mul_f32 v[184:185], v[108:109], v[84:85]
	v_pk_mul_f32 v[186:187], v[110:111], v[90:91]
	v_cvt_pk_bf16_f32 v184, v184, v185
	s_nop 0
	v_cvt_pk_bf16_f32 v185, v186, v187
	v_pk_mul_f32 v[124:125], v[84:85], v[168:169]
	v_pk_mul_f32 v[126:127], v[90:91], v[170:171]
	v_cvt_pk_bf16_f32 v186, v124, v125
	s_nop 0
	v_cvt_pk_bf16_f32 v187, v126, v127
	v_pk_mul_f32 v[84:85], v[12:13], v[78:79] op_sel_hi:[1,0]
	v_pk_mul_f32 v[90:91], v[14:15], v[78:79] op_sel_hi:[1,0]
	v_pk_mul_f32 v[188:189], v[112:113], v[84:85]
	v_pk_mul_f32 v[190:191], v[114:115], v[90:91]
	v_cvt_pk_bf16_f32 v188, v188, v189
	s_nop 0
	v_cvt_pk_bf16_f32 v189, v190, v191
	v_pk_mul_f32 v[124:125], v[84:85], v[172:173]
	v_pk_mul_f32 v[126:127], v[90:91], v[174:175]
	v_cvt_pk_bf16_f32 v190, v124, v125
	s_nop 0
	v_cvt_pk_bf16_f32 v191, v126, v127
	v_pk_mul_f32 v[84:85], v[8:9], v[78:79] op_sel_hi:[1,0]
	v_pk_mul_f32 v[90:91], v[10:11], v[78:79] op_sel_hi:[1,0]
	v_pk_mul_f32 v[192:193], v[116:117], v[84:85]
	v_pk_mul_f32 v[194:195], v[118:119], v[90:91]
	v_cvt_pk_bf16_f32 v192, v192, v193
	s_nop 0
	v_cvt_pk_bf16_f32 v193, v194, v195
	v_pk_mul_f32 v[124:125], v[84:85], v[176:177]
	v_pk_mul_f32 v[126:127], v[90:91], v[178:179]
	v_cvt_pk_bf16_f32 v194, v124, v125
	s_nop 0
	v_cvt_pk_bf16_f32 v195, v126, v127
	v_pk_mul_f32 v[84:85], v[4:5], v[78:79] op_sel_hi:[1,0]
	v_pk_mul_f32 v[90:91], v[6:7], v[78:79] op_sel_hi:[1,0]
	v_pk_mul_f32 v[92:93], v[120:121], v[84:85]
	v_pk_mul_f32 v[94:95], v[122:123], v[90:91]
	v_cvt_pk_bf16_f32 v92, v92, v93
	s_nop 0
	v_cvt_pk_bf16_f32 v93, v94, v95
	v_pk_mul_f32 v[124:125], v[84:85], v[180:181]
	v_pk_mul_f32 v[126:127], v[90:91], v[182:183]
	v_cvt_pk_bf16_f32 v94, v124, v125
	s_nop 0
	v_cvt_pk_bf16_f32 v95, v126, v127
	v_add_u32_e32 v38, s33, v38
	s_nop 0
	v_readfirstlane_b32 s0, v38
	s_cmpk_gt_i32 s0, 0x1fff
	s_cbranch_scc1 .Lnp_B_last
	v_ashrrev_i32_e32 v39, 31, v38
	v_lshlrev_b64 v[72:73], 13, v[38:39]
	v_lshl_add_u64 v[66:67], v[44:45], 0, v[72:73]
	s_movk_i32 s0, 0x1000
	s_mov_b32 s1, 0
	v_lshl_add_u64 v[68:69], v[66:67], 0, s[0:1]
	global_load_dwordx4 v[34:37], v[66:67], off
	global_load_dwordx4 v[30:33], v[66:67], off offset:1024
	global_load_dwordx4 v[24:27], v[66:67], off offset:2048
	global_load_dwordx4 v[20:23], v[66:67], off offset:3072
	global_load_dwordx4 v[16:19], v[68:69], off
	global_load_dwordx4 v[12:15], v[68:69], off offset:1024
	global_load_dwordx4 v[8:11], v[68:69], off offset:2048
	global_load_dwordx4 v[4:7], v[68:69], off offset:3072
	global_store_dwordx2 v[76:77], v[130:131], off
	global_store_dwordx2 v[128:129], v[132:133], off
	global_store_dwordx2 v[76:77], v[134:135], off offset:512
	global_store_dwordx2 v[128:129], v[136:137], off offset:512
	global_store_dwordx2 v[76:77], v[138:139], off offset:1024
	global_store_dwordx2 v[128:129], v[140:141], off offset:1024
	global_store_dwordx2 v[76:77], v[142:143], off offset:1536
	global_store_dwordx2 v[128:129], v[144:145], off offset:1536
	global_store_dwordx2 v[76:77], v[184:185], off offset:2048
	global_store_dwordx2 v[128:129], v[186:187], off offset:2048
	global_store_dwordx2 v[76:77], v[188:189], off offset:2560
	global_store_dwordx2 v[128:129], v[190:191], off offset:2560
	global_store_dwordx2 v[76:77], v[192:193], off offset:3072
	global_store_dwordx2 v[128:129], v[194:195], off offset:3072
	global_store_dwordx2 v[76:77], v[92:93], off offset:3584
	global_store_dwordx2 v[128:129], v[94:95], off offset:3584
	s_waitcnt vmcnt(16)
	s_branch .Lnp_B_body
.Lnp_B_last:
	global_store_dwordx2 v[76:77], v[130:131], off
	global_store_dwordx2 v[128:129], v[132:133], off
	global_store_dwordx2 v[76:77], v[134:135], off offset:512
	global_store_dwordx2 v[128:129], v[136:137], off offset:512
	global_store_dwordx2 v[76:77], v[138:139], off offset:1024
	global_store_dwordx2 v[128:129], v[140:141], off offset:1024
	global_store_dwordx2 v[76:77], v[142:143], off offset:1536
	global_store_dwordx2 v[128:129], v[144:145], off offset:1536
	global_store_dwordx2 v[76:77], v[184:185], off offset:2048
	global_store_dwordx2 v[128:129], v[186:187], off offset:2048
	global_store_dwordx2 v[76:77], v[188:189], off offset:2560
	global_store_dwordx2 v[128:129], v[190:191], off offset:2560
	global_store_dwordx2 v[76:77], v[192:193], off offset:3072
	global_store_dwordx2 v[128:129], v[194:195], off offset:3072
	global_store_dwordx2 v[76:77], v[92:93], off offset:3584
	global_store_dwordx2 v[128:129], v[94:95], off offset:3584
	s_branch .LBB0_780
.Lnp_C_body:
	v_pk_mul_f32 v[74:75], v[34:35], v[34:35]
	v_pk_fma_f32 v[74:75], v[36:37], v[36:37], v[74:75]
	v_pk_fma_f32 v[74:75], v[30:31], v[30:31], v[74:75]
	v_pk_fma_f32 v[74:75], v[32:33], v[32:33], v[74:75]
	v_pk_fma_f32 v[74:75], v[24:25], v[24:25], v[74:75]
	v_pk_fma_f32 v[74:75], v[26:27], v[26:27], v[74:75]
	v_pk_fma_f32 v[74:75], v[20:21], v[20:21], v[74:75]
	v_pk_fma_f32 v[74:75], v[22:23], v[22:23], v[74:75]
	v_pk_fma_f32 v[74:75], v[16:17], v[16:17], v[74:75]
	v_pk_fma_f32 v[74:75], v[18:19], v[18:19], v[74:75]
	v_pk_fma_f32 v[74:75], v[12:13], v[12:13], v[74:75]
	v_pk_fma_f32 v[74:75], v[14:15], v[14:15], v[74:75]
	v_pk_fma_f32 v[74:75], v[8:9], v[8:9], v[74:75]
	v_pk_fma_f32 v[74:75], v[10:11], v[10:11], v[74:75]
	v_pk_fma_f32 v[74:75], v[4:5], v[4:5], v[74:75]
	v_pk_fma_f32 v[74:75], v[6:7], v[6:7], v[74:75]
	v_add_f32_e32 v65, v74, v75
	ds_bpermute_b32 v67, v29, v65
	s_waitcnt lgkmcnt(0)
	v_add_f32_e32 v65, v65, v67
	ds_bpermute_b32 v67, v41, v65
	s_waitcnt lgkmcnt(0)
	v_add_f32_e32 v65, v65, v67
	ds_bpermute_b32 v67, v86, v65
	s_waitcnt lgkmcnt(0)
	v_add_f32_e32 v65, v65, v67
	ds_bpermute_b32 v67, v87, v65
	s_waitcnt lgkmcnt(0)
	v_add_f32_e32 v65, v65, v67
	ds_bpermute_b32 v67, v88, v65
	s_waitcnt lgkmcnt(0)
	v_add_f32_e32 v65, v65, v67
	ds_bpermute_b32 v67, v89, v65
	s_waitcnt lgkmcnt(0)
	v_add_f32_e32 v65, v65, v67
	v_fmamk_f32 v65, v65, 0x3a000000, v148
	v_mul_f32_e32 v67, 0x4b800000, v65
	v_cmp_gt_f32_e64 s[0:1], s81, v65
	s_nop 1
	v_cndmask_b32_e64 v65, v65, v67, s[0:1]
	v_rsq_f32_e32 v65, v65
	s_nop 0
	v_mul_f32_e32 v67, 0x45800000, v65
	v_cndmask_b32_e64 v78, v65, v67, s[0:1]
	v_lshl_add_u64 v[76:77], s[14:15], 0, v[72:73]
	v_lshl_add_u64 v[76:77], v[76:77], 0, v[80:81]
	s_movk_i32 s0, 0x1000
	s_mov_b32 s1, 0
	v_lshl_add_u64 v[128:129], v[76:77], 0, s[0:1]
	v_pk_mul_f32 v[84:85], v[34:35], v[78:79] op_sel_hi:[1,0]
	v_pk_mul_f32 v[90:91], v[36:37], v[78:79] op_sel_hi:[1,0]
	v_pk_mul_f32 v[130:131], v[0:1], v[84:85]
	v_pk_mul_f32 v[132:133], v[2:3], v[90:91]
	v_pk_mul_f32 v[84:85], v[30:31], v[78:79] op_sel_hi:[1,0]
	v_pk_mul_f32 v[90:91], v[32:33], v[78:79] op_sel_hi:[1,0]
	v_pk_mul_f32 v[134:135], v[96:97], v[84:85]
	v_pk_mul_f32 v[136:137], v[98:99], v[90:91]
	v_pk_mul_f32 v[84:85], v[24:25], v[78:79] op_sel_hi:[1,0]
	v_pk_mul_f32 v[90:91], v[26:27], v[78:79] op_sel_hi:[1,0]
	v_pk_mul_f32 v[138:139], v[100:101], v[84:85]
	v_pk_mul_f32 v[140:141], v[102:103], v[90:91]
	v_pk_mul_f32 v[84:85], v[20:21], v[78:79] op_sel_hi:[1,0]
	v_pk_mul_f32 v[90:91], v[22:23], v[78:79] op_sel_hi:[1,0]
	v_pk_mul_f32 v[142:143], v[104:105], v[84:85]
	v_pk_mul_f32 v[144:145], v[106:107], v[90:91]
	v_pk_mul_f32 v[84:85], v[16:17], v[78:79] op_sel_hi:[1,0]
	v_pk_mul_f32 v[90:91], v[18:19], v[78:79] op_sel_hi:[1,0]
	v_pk_mul_f32 v[184:185], v[108:109], v[84:85]
	v_pk_mul_f32 v[186:187], v[110:111], v[90:91]
	v_pk_mul_f32 v[84:85], v[12:13], v[78:79] op_sel_hi:[1,0]
	v_pk_mul_f32 v[90:91], v[14:15], v[78:79] op_sel_hi:[1,0]
	v_pk_mul_f32 v[188:189], v[112:113], v[84:85]
	v_pk_mul_f32 v[190:191], v[114:115], v[90:91]
	v_pk_mul_f32 v[84:85], v[8:9], v[78:79] op_sel_hi:[1,0]
	v_pk_mul_f32 v[90:91], v[10:11], v[78:79] op_sel_hi:[1,0]
	v_pk_mul_f32 v[192:193], v[116:117], v[84:85]
	v_pk_mul_f32 v[194:195], v[118:119], v[90:91]
	v_pk_mul_f32 v[84:85], v[4:5], v[78:79] op_sel_hi:[1,0]
	v_pk_mul_f32 v[90:91], v[6:7], v[78:79] op_sel_hi:[1,0]
	v_pk_mul_f32 v[92:93], v[120:121], v[84:85]
	v_pk_mul_f32 v[94:95], v[122:123], v[90:91]
	v_add_u32_e32 v38, s33, v38
	s_nop 0
	v_readfirstlane_b32 s0, v38
	s_cmpk_gt_i32 s0, 0x1fff
	s_cbranch_scc1 .Lnp_C_last
	v_ashrrev_i32_e32 v39, 31, v38
	v_lshlrev_b64 v[72:73], 13, v[38:39]
	v_lshl_add_u64 v[66:67], v[44:45], 0, v[72:73]
	s_movk_i32 s0, 0x1000
	s_mov_b32 s1, 0
	v_lshl_add_u64 v[68:69], v[66:67], 0, s[0:1]
	global_load_dwordx4 v[34:37], v[66:67], off
	global_load_dwordx4 v[30:33], v[66:67], off offset:1024
	global_load_dwordx4 v[24:27], v[66:67], off offset:2048
	global_load_dwordx4 v[20:23], v[66:67], off offset:3072
	global_load_dwordx4 v[16:19], v[68:69], off
	global_load_dwordx4 v[12:15], v[68:69], off offset:1024
	global_load_dwordx4 v[8:11], v[68:69], off offset:2048
	global_load_dwordx4 v[4:7], v[68:69], off offset:3072
	global_store_dwordx4 v[76:77], v[130:133], off
	global_store_dwordx4 v[76:77], v[134:137], off offset:1024
	global_store_dwordx4 v[76:77], v[138:141], off offset:2048
	global_store_dwordx4 v[76:77], v[142:145], off offset:3072
	global_store_dwordx4 v[128:129], v[184:187], off
	global_store_dwordx4 v[128:129], v[188:191], off offset:1024
	global_store_dwordx4 v[128:129], v[192:195], off offset:2048
	global_store_dwordx4 v[128:129], v[92:95], off offset:3072
	s_waitcnt vmcnt(8)
	s_branch .Lnp_C_body
.Lnp_C_last:
	global_store_dwordx4 v[76:77], v[130:133], off
	global_store_dwordx4 v[76:77], v[134:137], off offset:1024
	global_store_dwordx4 v[76:77], v[138:141], off offset:2048
	global_store_dwordx4 v[76:77], v[142:145], off offset:3072
	global_store_dwordx4 v[128:129], v[184:187], off
	global_store_dwordx4 v[128:129], v[188:191], off offset:1024
	global_store_dwordx4 v[128:129], v[192:195], off offset:2048
	global_store_dwordx4 v[128:129], v[92:95], off offset:3072
	s_branch .LBB0_780
